# v48 with the s_sleep between grid-barrier polls removed (spin-wait tuning)
# baseline (speedup 1.0000x reference)
; __global__ void __launch_bounds__(NTHREADS, 2) fwd_megakernel(Params P) {
;     ...
;     grid.sync();
.LBB0_139:
	global_load_dword v2, v0, s[4:5] offset:32 sc1
	s_waitcnt vmcnt(0)
	v_and_b32_e32 v2, 0xffff0000, v2
	v_cmp_ne_u32_e32 vcc, v2, v1
	s_or_b64 s[6:7], vcc, s[6:7]
	s_andn2_b64 exec, exec, s[6:7]
	s_cbranch_execnz .LBB0_139

; __device__ __forceinline__ unsigned xb_ld(unsigned* p)              { return __hip_atomic_load(p, __ATOMIC_RELAXED, __HIP_MEMORY_SCOPE_AGENT); }
; __device__ __forceinline__ void xcd_barrier_complete(unsigned* bar, unsigned x, unsigned& nloc, unsigned& nx) {
;     const unsigned G = gridDim.x * gridDim.y * gridDim.z;
;     unsigned sum, cnt, mine, sp = 0u;
;     for (;;) {
;         sum = 0u; cnt = 0u; mine = 0u;
; #pragma unroll
;         for (unsigned j = 0; j < 16; ++j) { const unsigned c = xb_ld(&bar[XB_XCNT(j)]); sum += c; cnt += (c > 0u) ? 1u : 0u; mine = (j == x) ? c : mine; }
;         if (sum == G) break;
;         __builtin_amdgcn_s_sleep(1);
;         if ((++sp & 255u) == 0u) { if (xb_ld(&bar[XB_TMO])) break; if (sp > XB_SPIN_CAP) { atomicAdd(&bar[XB_TMO], 1u); break; } }
;     }
;     nloc = mine > 0u ? mine : 1u; nx = cnt > 0u ? cnt : 1u;
; }
.LBB0_145:
	global_load_dword v15, v16, s[4:5] offset:1024 sc1
	s_waitcnt lgkmcnt(0)
	global_load_dword v0, v16, s[4:5] offset:1280 sc1
	global_load_dword v1, v16, s[4:5] offset:1536 sc1
	global_load_dword v2, v16, s[4:5] offset:1792 sc1
	global_load_dword v3, v16, s[4:5] offset:2048 sc1
	global_load_dword v4, v16, s[4:5] offset:2304 sc1
	global_load_dword v5, v16, s[4:5] offset:2560 sc1
	global_load_dword v6, v16, s[4:5] offset:2816 sc1
	global_load_dword v7, v16, s[4:5] offset:3072 sc1
	global_load_dword v8, v16, s[4:5] offset:3328 sc1
	global_load_dword v9, v16, s[4:5] offset:3584 sc1
	global_load_dword v10, v16, s[4:5] offset:3840 sc1
	global_load_dword v11, v16, s[6:7] sc1
	global_load_dword v12, v16, s[8:9] sc1
	global_load_dword v13, v16, s[16:17] sc1
	global_load_dword v14, v16, s[18:19] sc1
	s_mov_b64 s[36:37], -1
	s_mov_b64 s[38:39], -1
	s_waitcnt vmcnt(14)
	v_add_u32_e32 v17, v0, v15
	s_waitcnt vmcnt(13)
	v_add_u32_e32 v17, v17, v1
	s_waitcnt vmcnt(12)
	v_add_u32_e32 v17, v17, v2
	s_waitcnt vmcnt(11)
	v_add_u32_e32 v17, v17, v3
	s_waitcnt vmcnt(10)
	v_add_u32_e32 v17, v17, v4
	s_waitcnt vmcnt(9)
	v_add_u32_e32 v17, v17, v5
	s_waitcnt vmcnt(8)
	v_add_u32_e32 v17, v17, v6
	s_waitcnt vmcnt(7)
	v_add_u32_e32 v17, v17, v7
	s_waitcnt vmcnt(6)
	v_add_u32_e32 v17, v17, v8
	s_waitcnt vmcnt(5)
	v_add_u32_e32 v17, v17, v9
	s_waitcnt vmcnt(4)
	v_add_u32_e32 v17, v17, v10
	s_waitcnt vmcnt(3)
	v_add_u32_e32 v17, v17, v11
	s_waitcnt vmcnt(2)
	v_add_u32_e32 v17, v17, v12
	s_waitcnt vmcnt(1)
	v_add_u32_e32 v17, v17, v13
	s_waitcnt vmcnt(0)
	v_add_u32_e32 v17, v17, v14
	v_cmp_eq_u32_e32 vcc, s11, v17
	s_cbranch_vccnz .LBB0_144
	s_and_b32 s13, s12, 0xff
	s_cmp_eq_u32 s13, 0
	s_mov_b64 s[40:41], -1
	s_cbranch_scc1 .LBB0_149
	s_and_b64 vcc, exec, s[40:41]
	s_cbranch_vccz .LBB0_144

; __device__ __forceinline__ unsigned xb_ld(unsigned* p)              { return __hip_atomic_load(p, __ATOMIC_RELAXED, __HIP_MEMORY_SCOPE_AGENT); }
; __device__ __forceinline__ unsigned xb_add(unsigned* p, unsigned v) { return __hip_atomic_fetch_add(p, v, __ATOMIC_RELAXED, __HIP_MEMORY_SCOPE_AGENT); }
; #define XB_SPIN(cond, bar) do { unsigned _sp = 0; while (cond) { __builtin_amdgcn_s_sleep(1); \
;     if ((++_sp & 255u) == 0u) { if (xb_ld(&(bar)[XB_TMO])) break; if (_sp > XB_SPIN_CAP) { atomicAdd(&(bar)[XB_TMO], 1u); break; } } } } while (0)
; __device__ __forceinline__ void xcd_barrier(const XcdBarrier& b) {
;     ...
;             else XB_SPIN(xb_ld(&bar[XB_TOPGEN]) == tg, bar);
;             __builtin_amdgcn_fence(__ATOMIC_ACQUIRE, "agent");
;             xb_add(&bar[XB_XGEN(b.x)], 1u);
;             asm volatile("s_waitcnt vmcnt(0)" ::: "memory");
;         } else {
;             XB_SPIN(xb_ld(&bar[XB_XGEN(b.x)]) == gen, bar);
.LBB0_163:
	s_and_b32 s11, s10, 0xff
	s_mov_b64 s[40:41], -1
	s_cmp_lg_u32 s11, 0
	s_mov_b64 s[44:45], -1
	s_cbranch_scc0 .LBB0_166
	s_and_b64 vcc, exec, s[44:45]
	s_cbranch_vccz .LBB0_162

; __device__ __forceinline__ unsigned xb_ld(unsigned* p)              { return __hip_atomic_load(p, __ATOMIC_RELAXED, __HIP_MEMORY_SCOPE_AGENT); }
; __device__ __forceinline__ unsigned xb_add(unsigned* p, unsigned v) { return __hip_atomic_fetch_add(p, v, __ATOMIC_RELAXED, __HIP_MEMORY_SCOPE_AGENT); }
; #define XB_SPIN(cond, bar) do { unsigned _sp = 0; while (cond) { __builtin_amdgcn_s_sleep(1); \
;     if ((++_sp & 255u) == 0u) { if (xb_ld(&(bar)[XB_TMO])) break; if (_sp > XB_SPIN_CAP) { atomicAdd(&(bar)[XB_TMO], 1u); break; } } } } while (0)
; __device__ __forceinline__ void xcd_barrier(const XcdBarrier& b) {
;     ...
;             else XB_SPIN(xb_ld(&bar[XB_TOPGEN]) == tg, bar);
;             __builtin_amdgcn_fence(__ATOMIC_ACQUIRE, "agent");
;             xb_add(&bar[XB_XGEN(b.x)], 1u);
;             asm volatile("s_waitcnt vmcnt(0)" ::: "memory");
;         } else {
;             XB_SPIN(xb_ld(&bar[XB_XGEN(b.x)]) == gen, bar);
.LBB0_180:
	s_and_b32 s11, s10, 0xff
	s_cmp_lg_u32 s11, 0
	s_mov_b64 s[42:43], -1
	s_cbranch_scc0 .LBB0_183
	s_mov_b64 s[44:45], -1
	s_and_b64 vcc, exec, s[42:43]
	s_cbranch_vccz .LBB0_179

; __device__ __forceinline__ unsigned xb_ld(unsigned* p)              { return __hip_atomic_load(p, __ATOMIC_RELAXED, __HIP_MEMORY_SCOPE_AGENT); }
; __device__ __forceinline__ void xcd_barrier_complete(unsigned* bar, unsigned x, unsigned& nloc, unsigned& nx) {
;     const unsigned G = gridDim.x * gridDim.y * gridDim.z;
;     unsigned sum, cnt, mine, sp = 0u;
;     for (;;) {
;         sum = 0u; cnt = 0u; mine = 0u;
; #pragma unroll
;         for (unsigned j = 0; j < 16; ++j) { const unsigned c = xb_ld(&bar[XB_XCNT(j)]); sum += c; cnt += (c > 0u) ? 1u : 0u; mine = (j == x) ? c : mine; }
;         if (sum == G) break;
;         __builtin_amdgcn_s_sleep(1);
;         if ((++sp & 255u) == 0u) { if (xb_ld(&bar[XB_TMO])) break; if (sp > XB_SPIN_CAP) { atomicAdd(&bar[XB_TMO], 1u); break; } }
;     }
;     nloc = mine > 0u ? mine : 1u; nx = cnt > 0u ? cnt : 1u;
; }
.LBB0_207:
	global_load_dword v16, v1, s[4:5] offset:1024 sc1
	global_load_dword v0, v1, s[4:5] offset:1280 sc1
	s_waitcnt lgkmcnt(0)
	global_load_dword v2, v1, s[4:5] offset:1536 sc1
	global_load_dword v3, v1, s[4:5] offset:1792 sc1
	global_load_dword v4, v1, s[4:5] offset:2048 sc1
	global_load_dword v5, v1, s[4:5] offset:2304 sc1
	global_load_dword v6, v1, s[4:5] offset:2560 sc1
	global_load_dword v7, v1, s[4:5] offset:2816 sc1
	global_load_dword v8, v1, s[4:5] offset:3072 sc1
	global_load_dword v9, v1, s[4:5] offset:3328 sc1
	global_load_dword v10, v1, s[4:5] offset:3584 sc1
	global_load_dword v11, v1, s[4:5] offset:3840 sc1
	global_load_dword v12, v1, s[8:9] sc1
	global_load_dword v13, v1, s[28:29] sc1
	global_load_dword v14, v1, s[40:41] sc1
	global_load_dword v15, v1, s[42:43] sc1
	s_mov_b64 s[44:45], -1
	s_mov_b64 s[68:69], -1
	s_waitcnt vmcnt(14)
	v_add_u32_e32 v17, v0, v16
	s_waitcnt vmcnt(13)
	v_add_u32_e32 v17, v17, v2
	s_waitcnt vmcnt(12)
	v_add_u32_e32 v17, v17, v3
	s_waitcnt vmcnt(11)
	v_add_u32_e32 v17, v17, v4
	s_waitcnt vmcnt(10)
	v_add_u32_e32 v17, v17, v5
	s_waitcnt vmcnt(9)
	v_add_u32_e32 v17, v17, v6
	s_waitcnt vmcnt(8)
	v_add_u32_e32 v17, v17, v7
	s_waitcnt vmcnt(7)
	v_add_u32_e32 v17, v17, v8
	s_waitcnt vmcnt(6)
	v_add_u32_e32 v17, v17, v9
	s_waitcnt vmcnt(5)
	v_add_u32_e32 v17, v17, v10
	s_waitcnt vmcnt(4)
	v_add_u32_e32 v17, v17, v11
	s_waitcnt vmcnt(3)
	v_add_u32_e32 v17, v17, v12
	s_waitcnt vmcnt(2)
	v_add_u32_e32 v17, v17, v13
	s_waitcnt vmcnt(1)
	v_add_u32_e32 v17, v17, v14
	s_waitcnt vmcnt(0)
	v_add_u32_e32 v17, v17, v15
	v_cmp_eq_u32_e32 vcc, s35, v17
	s_cbranch_vccnz .LBB0_206
	s_and_b32 s14, s11, 0xff
	s_cmp_eq_u32 s14, 0
	s_mov_b64 s[72:73], -1
	s_cbranch_scc1 .LBB0_211
	s_and_b64 vcc, exec, s[72:73]
	s_cbranch_vccz .LBB0_206

; __device__ __forceinline__ unsigned xb_ld(unsigned* p)              { return __hip_atomic_load(p, __ATOMIC_RELAXED, __HIP_MEMORY_SCOPE_AGENT); }
; __device__ __forceinline__ unsigned xb_add(unsigned* p, unsigned v) { return __hip_atomic_fetch_add(p, v, __ATOMIC_RELAXED, __HIP_MEMORY_SCOPE_AGENT); }
; #define XB_SPIN(cond, bar) do { unsigned _sp = 0; while (cond) { __builtin_amdgcn_s_sleep(1); \
;     if ((++_sp & 255u) == 0u) { if (xb_ld(&(bar)[XB_TMO])) break; if (_sp > XB_SPIN_CAP) { atomicAdd(&(bar)[XB_TMO], 1u); break; } } } } while (0)
; __device__ __forceinline__ void xcd_barrier(const XcdBarrier& b) {
;     ...
;             else XB_SPIN(xb_ld(&bar[XB_TOPGEN]) == tg, bar);
;             __builtin_amdgcn_fence(__ATOMIC_ACQUIRE, "agent");
;             xb_add(&bar[XB_XGEN(b.x)], 1u);
;             asm volatile("s_waitcnt vmcnt(0)" ::: "memory");
;         } else {
;             XB_SPIN(xb_ld(&bar[XB_XGEN(b.x)]) == gen, bar);
.LBB0_225:
	s_and_b32 s11, s10, 0xff
	s_mov_b64 s[72:73], -1
	s_cmp_lg_u32 s11, 0
	s_mov_b64 s[76:77], -1
	s_cbranch_scc0 .LBB0_228
	s_and_b64 vcc, exec, s[76:77]
	s_cbranch_vccz .LBB0_224

; __device__ __forceinline__ unsigned xb_ld(unsigned* p)              { return __hip_atomic_load(p, __ATOMIC_RELAXED, __HIP_MEMORY_SCOPE_AGENT); }
; __device__ __forceinline__ void xcd_barrier_complete(unsigned* bar, unsigned x, unsigned& nloc, unsigned& nx) {
;     const unsigned G = gridDim.x * gridDim.y * gridDim.z;
;     unsigned sum, cnt, mine, sp = 0u;
;     for (;;) {
;         sum = 0u; cnt = 0u; mine = 0u;
; #pragma unroll
;         for (unsigned j = 0; j < 16; ++j) { const unsigned c = xb_ld(&bar[XB_XCNT(j)]); sum += c; cnt += (c > 0u) ? 1u : 0u; mine = (j == x) ? c : mine; }
;         if (sum == G) break;
;         __builtin_amdgcn_s_sleep(1);
;         if ((++sp & 255u) == 0u) { if (xb_ld(&bar[XB_TMO])) break; if (sp > XB_SPIN_CAP) { atomicAdd(&bar[XB_TMO], 1u); break; } }
;     }
;     nloc = mine > 0u ? mine : 1u; nx = cnt > 0u ? cnt : 1u;
; }
.LBB0_297:
	global_load_dword v16, v1, s[4:5] offset:1024 sc1
	global_load_dword v0, v1, s[4:5] offset:1280 sc1
	s_waitcnt lgkmcnt(0)
	global_load_dword v2, v1, s[4:5] offset:1536 sc1
	global_load_dword v3, v1, s[4:5] offset:1792 sc1
	global_load_dword v4, v1, s[4:5] offset:2048 sc1
	global_load_dword v5, v1, s[4:5] offset:2304 sc1
	global_load_dword v6, v1, s[4:5] offset:2560 sc1
	global_load_dword v7, v1, s[4:5] offset:2816 sc1
	global_load_dword v8, v1, s[4:5] offset:3072 sc1
	global_load_dword v9, v1, s[4:5] offset:3328 sc1
	global_load_dword v10, v1, s[4:5] offset:3584 sc1
	global_load_dword v11, v1, s[4:5] offset:3840 sc1
	global_load_dword v12, v1, s[6:7] sc1
	global_load_dword v13, v1, s[28:29] sc1
	global_load_dword v14, v1, s[40:41] sc1
	global_load_dword v15, v1, s[42:43] sc1
	s_mov_b64 s[44:45], -1
	s_mov_b64 s[68:69], -1
	s_waitcnt vmcnt(14)
	v_add_u32_e32 v17, v0, v16
	s_waitcnt vmcnt(13)
	v_add_u32_e32 v17, v17, v2
	s_waitcnt vmcnt(12)
	v_add_u32_e32 v17, v17, v3
	s_waitcnt vmcnt(11)
	v_add_u32_e32 v17, v17, v4
	s_waitcnt vmcnt(10)
	v_add_u32_e32 v17, v17, v5
	s_waitcnt vmcnt(9)
	v_add_u32_e32 v17, v17, v6
	s_waitcnt vmcnt(8)
	v_add_u32_e32 v17, v17, v7
	s_waitcnt vmcnt(7)
	v_add_u32_e32 v17, v17, v8
	s_waitcnt vmcnt(6)
	v_add_u32_e32 v17, v17, v9
	s_waitcnt vmcnt(5)
	v_add_u32_e32 v17, v17, v10
	s_waitcnt vmcnt(4)
	v_add_u32_e32 v17, v17, v11
	s_waitcnt vmcnt(3)
	v_add_u32_e32 v17, v17, v12
	s_waitcnt vmcnt(2)
	v_add_u32_e32 v17, v17, v13
	s_waitcnt vmcnt(1)
	v_add_u32_e32 v17, v17, v14
	s_waitcnt vmcnt(0)
	v_add_u32_e32 v17, v17, v15
	v_cmp_eq_u32_e32 vcc, s35, v17
	s_cbranch_vccnz .LBB0_296
	s_and_b32 s16, s11, 0xff
	s_cmp_eq_u32 s16, 0
	s_mov_b64 s[78:79], -1
	s_cbranch_scc1 .LBB0_301
	s_and_b64 vcc, exec, s[78:79]
	s_cbranch_vccz .LBB0_296

; __device__ __forceinline__ unsigned xb_ld(unsigned* p)              { return __hip_atomic_load(p, __ATOMIC_RELAXED, __HIP_MEMORY_SCOPE_AGENT); }
; __device__ __forceinline__ unsigned xb_add(unsigned* p, unsigned v) { return __hip_atomic_fetch_add(p, v, __ATOMIC_RELAXED, __HIP_MEMORY_SCOPE_AGENT); }
; #define XB_SPIN(cond, bar) do { unsigned _sp = 0; while (cond) { __builtin_amdgcn_s_sleep(1); \
;     if ((++_sp & 255u) == 0u) { if (xb_ld(&(bar)[XB_TMO])) break; if (_sp > XB_SPIN_CAP) { atomicAdd(&(bar)[XB_TMO], 1u); break; } } } } while (0)
; __device__ __forceinline__ void xcd_barrier(const XcdBarrier& b) {
;     ...
;             else XB_SPIN(xb_ld(&bar[XB_TOPGEN]) == tg, bar);
;             __builtin_amdgcn_fence(__ATOMIC_ACQUIRE, "agent");
;             xb_add(&bar[XB_XGEN(b.x)], 1u);
;             asm volatile("s_waitcnt vmcnt(0)" ::: "memory");
;         } else {
;             XB_SPIN(xb_ld(&bar[XB_XGEN(b.x)]) == gen, bar);
.LBB0_315:
	s_and_b32 s11, s10, 0xff
	s_mov_b64 s[78:79], -1
	s_cmp_lg_u32 s11, 0
	s_mov_b64 s[84:85], -1
	s_cbranch_scc0 .LBB0_318
	s_and_b64 vcc, exec, s[84:85]
	s_cbranch_vccz .LBB0_314

; __device__ __forceinline__ unsigned xb_ld(unsigned* p)              { return __hip_atomic_load(p, __ATOMIC_RELAXED, __HIP_MEMORY_SCOPE_AGENT); }
; __device__ __forceinline__ void xcd_barrier_complete(unsigned* bar, unsigned x, unsigned& nloc, unsigned& nx) {
;     const unsigned G = gridDim.x * gridDim.y * gridDim.z;
;     unsigned sum, cnt, mine, sp = 0u;
;     for (;;) {
;         sum = 0u; cnt = 0u; mine = 0u;
; #pragma unroll
;         for (unsigned j = 0; j < 16; ++j) { const unsigned c = xb_ld(&bar[XB_XCNT(j)]); sum += c; cnt += (c > 0u) ? 1u : 0u; mine = (j == x) ? c : mine; }
;         if (sum == G) break;
;         __builtin_amdgcn_s_sleep(1);
;         if ((++sp & 255u) == 0u) { if (xb_ld(&bar[XB_TMO])) break; if (sp > XB_SPIN_CAP) { atomicAdd(&bar[XB_TMO], 1u); break; } }
;     }
;     nloc = mine > 0u ? mine : 1u; nx = cnt > 0u ? cnt : 1u;
; }
.LBB0_366:
	global_load_dword v16, v1, s[6:7] offset:1024 sc1
	global_load_dword v0, v1, s[6:7] offset:1280 sc1
	s_waitcnt lgkmcnt(0)
	global_load_dword v2, v1, s[6:7] offset:1536 sc1
	global_load_dword v3, v1, s[6:7] offset:1792 sc1
	global_load_dword v4, v1, s[6:7] offset:2048 sc1
	global_load_dword v5, v1, s[6:7] offset:2304 sc1
	global_load_dword v6, v1, s[6:7] offset:2560 sc1
	global_load_dword v7, v1, s[6:7] offset:2816 sc1
	global_load_dword v8, v1, s[6:7] offset:3072 sc1
	global_load_dword v9, v1, s[6:7] offset:3328 sc1
	global_load_dword v10, v1, s[6:7] offset:3584 sc1
	global_load_dword v11, v1, s[6:7] offset:3840 sc1
	global_load_dword v12, v1, s[28:29] sc1
	global_load_dword v13, v1, s[40:41] sc1
	global_load_dword v14, v1, s[42:43] sc1
	global_load_dword v15, v1, s[44:45] sc1
	s_mov_b64 s[68:69], -1
	s_mov_b64 s[78:79], -1
	s_waitcnt vmcnt(14)
	v_add_u32_e32 v17, v0, v16
	s_waitcnt vmcnt(13)
	v_add_u32_e32 v17, v17, v2
	s_waitcnt vmcnt(12)
	v_add_u32_e32 v17, v17, v3
	s_waitcnt vmcnt(11)
	v_add_u32_e32 v17, v17, v4
	s_waitcnt vmcnt(10)
	v_add_u32_e32 v17, v17, v5
	s_waitcnt vmcnt(9)
	v_add_u32_e32 v17, v17, v6
	s_waitcnt vmcnt(8)
	v_add_u32_e32 v17, v17, v7
	s_waitcnt vmcnt(7)
	v_add_u32_e32 v17, v17, v8
	s_waitcnt vmcnt(6)
	v_add_u32_e32 v17, v17, v9
	s_waitcnt vmcnt(5)
	v_add_u32_e32 v17, v17, v10
	s_waitcnt vmcnt(4)
	v_add_u32_e32 v17, v17, v11
	s_waitcnt vmcnt(3)
	v_add_u32_e32 v17, v17, v12
	s_waitcnt vmcnt(2)
	v_add_u32_e32 v17, v17, v13
	s_waitcnt vmcnt(1)
	v_add_u32_e32 v17, v17, v14
	s_waitcnt vmcnt(0)
	v_add_u32_e32 v17, v17, v15
	v_cmp_eq_u32_e32 vcc, s35, v17
	s_cbranch_vccnz .LBB0_365
	s_and_b32 s16, s11, 0xff
	s_cmp_eq_u32 s16, 0
	s_mov_b64 s[82:83], -1
	s_cbranch_scc1 .LBB0_370
	s_and_b64 vcc, exec, s[82:83]
	s_cbranch_vccz .LBB0_365

; __device__ __forceinline__ unsigned xb_ld(unsigned* p)              { return __hip_atomic_load(p, __ATOMIC_RELAXED, __HIP_MEMORY_SCOPE_AGENT); }
; __device__ __forceinline__ unsigned xb_add(unsigned* p, unsigned v) { return __hip_atomic_fetch_add(p, v, __ATOMIC_RELAXED, __HIP_MEMORY_SCOPE_AGENT); }
; #define XB_SPIN(cond, bar) do { unsigned _sp = 0; while (cond) { __builtin_amdgcn_s_sleep(1); \
;     if ((++_sp & 255u) == 0u) { if (xb_ld(&(bar)[XB_TMO])) break; if (_sp > XB_SPIN_CAP) { atomicAdd(&(bar)[XB_TMO], 1u); break; } } } } while (0)
; __device__ __forceinline__ void xcd_barrier(const XcdBarrier& b) {
;     ...
;             else XB_SPIN(xb_ld(&bar[XB_TOPGEN]) == tg, bar);
;             __builtin_amdgcn_fence(__ATOMIC_ACQUIRE, "agent");
;             xb_add(&bar[XB_XGEN(b.x)], 1u);
;             asm volatile("s_waitcnt vmcnt(0)" ::: "memory");
;         } else {
;             XB_SPIN(xb_ld(&bar[XB_XGEN(b.x)]) == gen, bar);
.LBB0_384:
	s_and_b32 s11, s10, 0xff
	s_mov_b64 s[82:83], -1
	s_cmp_lg_u32 s11, 0
	s_mov_b64 s[86:87], -1
	s_cbranch_scc0 .LBB0_387
	s_and_b64 vcc, exec, s[86:87]
	s_cbranch_vccz .LBB0_383

; __device__ __forceinline__ unsigned xb_ld(unsigned* p)              { return __hip_atomic_load(p, __ATOMIC_RELAXED, __HIP_MEMORY_SCOPE_AGENT); }
; __device__ __forceinline__ void xcd_barrier_complete(unsigned* bar, unsigned x, unsigned& nloc, unsigned& nx) {
;     const unsigned G = gridDim.x * gridDim.y * gridDim.z;
;     unsigned sum, cnt, mine, sp = 0u;
;     for (;;) {
;         sum = 0u; cnt = 0u; mine = 0u;
; #pragma unroll
;         for (unsigned j = 0; j < 16; ++j) { const unsigned c = xb_ld(&bar[XB_XCNT(j)]); sum += c; cnt += (c > 0u) ? 1u : 0u; mine = (j == x) ? c : mine; }
;         if (sum == G) break;
;         __builtin_amdgcn_s_sleep(1);
;         if ((++sp & 255u) == 0u) { if (xb_ld(&bar[XB_TMO])) break; if (sp > XB_SPIN_CAP) { atomicAdd(&bar[XB_TMO], 1u); break; } }
;     }
;     nloc = mine > 0u ? mine : 1u; nx = cnt > 0u ? cnt : 1u;
; }
.LBB0_655:
	global_load_dword v16, v1, s[6:7] offset:1024 sc1
	global_load_dword v0, v1, s[6:7] offset:1280 sc1
	s_waitcnt lgkmcnt(0)
	global_load_dword v2, v1, s[6:7] offset:1536 sc1
	global_load_dword v3, v1, s[6:7] offset:1792 sc1
	global_load_dword v4, v1, s[6:7] offset:2048 sc1
	global_load_dword v5, v1, s[6:7] offset:2304 sc1
	global_load_dword v6, v1, s[6:7] offset:2560 sc1
	global_load_dword v7, v1, s[6:7] offset:2816 sc1
	global_load_dword v8, v1, s[6:7] offset:3072 sc1
	global_load_dword v9, v1, s[6:7] offset:3328 sc1
	global_load_dword v10, v1, s[6:7] offset:3584 sc1
	global_load_dword v11, v1, s[6:7] offset:3840 sc1
	global_load_dword v12, v1, s[8:9] sc1
	global_load_dword v13, v1, s[28:29] sc1
	global_load_dword v14, v1, s[40:41] sc1
	global_load_dword v15, v1, s[42:43] sc1
	s_mov_b64 s[44:45], -1
	s_mov_b64 s[68:69], -1
	s_waitcnt vmcnt(14)
	v_add_u32_e32 v17, v0, v16
	s_waitcnt vmcnt(13)
	v_add_u32_e32 v17, v17, v2
	s_waitcnt vmcnt(12)
	v_add_u32_e32 v17, v17, v3
	s_waitcnt vmcnt(11)
	v_add_u32_e32 v17, v17, v4
	s_waitcnt vmcnt(10)
	v_add_u32_e32 v17, v17, v5
	s_waitcnt vmcnt(9)
	v_add_u32_e32 v17, v17, v6
	s_waitcnt vmcnt(8)
	v_add_u32_e32 v17, v17, v7
	s_waitcnt vmcnt(7)
	v_add_u32_e32 v17, v17, v8
	s_waitcnt vmcnt(6)
	v_add_u32_e32 v17, v17, v9
	s_waitcnt vmcnt(5)
	v_add_u32_e32 v17, v17, v10
	s_waitcnt vmcnt(4)
	v_add_u32_e32 v17, v17, v11
	s_waitcnt vmcnt(3)
	v_add_u32_e32 v17, v17, v12
	s_waitcnt vmcnt(2)
	v_add_u32_e32 v17, v17, v13
	s_waitcnt vmcnt(1)
	v_add_u32_e32 v17, v17, v14
	s_waitcnt vmcnt(0)
	v_add_u32_e32 v17, v17, v15
	v_cmp_eq_u32_e32 vcc, s35, v17
	s_cbranch_vccnz .LBB0_654
	s_and_b32 s14, s11, 0xff
	s_cmp_eq_u32 s14, 0
	s_mov_b64 s[78:79], -1
	s_cbranch_scc1 .LBB0_659
	s_and_b64 vcc, exec, s[78:79]
	s_cbranch_vccz .LBB0_654

; __device__ __forceinline__ unsigned xb_ld(unsigned* p)              { return __hip_atomic_load(p, __ATOMIC_RELAXED, __HIP_MEMORY_SCOPE_AGENT); }
; __device__ __forceinline__ void xcd_barrier_complete(unsigned* bar, unsigned x, unsigned& nloc, unsigned& nx) {
;     const unsigned G = gridDim.x * gridDim.y * gridDim.z;
;     unsigned sum, cnt, mine, sp = 0u;
;     for (;;) {
;         sum = 0u; cnt = 0u; mine = 0u;
; #pragma unroll
;         for (unsigned j = 0; j < 16; ++j) { const unsigned c = xb_ld(&bar[XB_XCNT(j)]); sum += c; cnt += (c > 0u) ? 1u : 0u; mine = (j == x) ? c : mine; }
;         if (sum == G) break;
;         __builtin_amdgcn_s_sleep(1);
;         if ((++sp & 255u) == 0u) { if (xb_ld(&bar[XB_TMO])) break; if (sp > XB_SPIN_CAP) { atomicAdd(&bar[XB_TMO], 1u); break; } }
;     }
;     nloc = mine > 0u ? mine : 1u; nx = cnt > 0u ? cnt : 1u;
; }
.LBB0_875:
	global_load_dword v16, v1, s[4:5] offset:1024 sc1
	global_load_dword v0, v1, s[4:5] offset:1280 sc1
	s_waitcnt lgkmcnt(0)
	global_load_dword v2, v1, s[4:5] offset:1536 sc1
	global_load_dword v3, v1, s[4:5] offset:1792 sc1
	global_load_dword v4, v1, s[4:5] offset:2048 sc1
	global_load_dword v5, v1, s[4:5] offset:2304 sc1
	global_load_dword v6, v1, s[4:5] offset:2560 sc1
	global_load_dword v7, v1, s[4:5] offset:2816 sc1
	global_load_dword v8, v1, s[4:5] offset:3072 sc1
	global_load_dword v9, v1, s[4:5] offset:3328 sc1
	global_load_dword v10, v1, s[4:5] offset:3584 sc1
	global_load_dword v11, v1, s[4:5] offset:3840 sc1
	global_load_dword v12, v1, s[6:7] sc1
	global_load_dword v13, v1, s[8:9] sc1
	global_load_dword v14, v1, s[28:29] sc1
	global_load_dword v15, v1, s[40:41] sc1
	s_mov_b64 s[42:43], -1
	s_mov_b64 s[44:45], -1
	s_waitcnt vmcnt(14)
	v_add_u32_e32 v17, v0, v16
	s_waitcnt vmcnt(13)
	v_add_u32_e32 v17, v17, v2
	s_waitcnt vmcnt(12)
	v_add_u32_e32 v17, v17, v3
	s_waitcnt vmcnt(11)
	v_add_u32_e32 v17, v17, v4
	s_waitcnt vmcnt(10)
	v_add_u32_e32 v17, v17, v5
	s_waitcnt vmcnt(9)
	v_add_u32_e32 v17, v17, v6
	s_waitcnt vmcnt(8)
	v_add_u32_e32 v17, v17, v7
	s_waitcnt vmcnt(7)
	v_add_u32_e32 v17, v17, v8
	s_waitcnt vmcnt(6)
	v_add_u32_e32 v17, v17, v9
	s_waitcnt vmcnt(5)
	v_add_u32_e32 v17, v17, v10
	s_waitcnt vmcnt(4)
	v_add_u32_e32 v17, v17, v11
	s_waitcnt vmcnt(3)
	v_add_u32_e32 v17, v17, v12
	s_waitcnt vmcnt(2)
	v_add_u32_e32 v17, v17, v13
	s_waitcnt vmcnt(1)
	v_add_u32_e32 v17, v17, v14
	s_waitcnt vmcnt(0)
	v_add_u32_e32 v17, v17, v15
	v_cmp_eq_u32_e32 vcc, s35, v17
	s_cbranch_vccnz .LBB0_874
	s_and_b32 s14, s11, 0xff
	s_cmp_eq_u32 s14, 0
	s_mov_b64 s[68:69], -1
	s_cbranch_scc1 .LBB0_879
	s_and_b64 vcc, exec, s[68:69]
	s_cbranch_vccz .LBB0_874

; __device__ __forceinline__ unsigned xb_ld(unsigned* p)              { return __hip_atomic_load(p, __ATOMIC_RELAXED, __HIP_MEMORY_SCOPE_AGENT); }
; __device__ __forceinline__ unsigned xb_add(unsigned* p, unsigned v) { return __hip_atomic_fetch_add(p, v, __ATOMIC_RELAXED, __HIP_MEMORY_SCOPE_AGENT); }
; #define XB_SPIN(cond, bar) do { unsigned _sp = 0; while (cond) { __builtin_amdgcn_s_sleep(1); \
;     if ((++_sp & 255u) == 0u) { if (xb_ld(&(bar)[XB_TMO])) break; if (_sp > XB_SPIN_CAP) { atomicAdd(&(bar)[XB_TMO], 1u); break; } } } } while (0)
; __device__ __forceinline__ void xcd_barrier(const XcdBarrier& b) {
;     ...
;             else XB_SPIN(xb_ld(&bar[XB_TOPGEN]) == tg, bar);
;             __builtin_amdgcn_fence(__ATOMIC_ACQUIRE, "agent");
;             xb_add(&bar[XB_XGEN(b.x)], 1u);
;             asm volatile("s_waitcnt vmcnt(0)" ::: "memory");
;         } else {
;             XB_SPIN(xb_ld(&bar[XB_XGEN(b.x)]) == gen, bar);
.LBB0_893:
	s_and_b32 s11, s10, 0xff
	s_mov_b64 s[68:69], -1
	s_cmp_lg_u32 s11, 0
	s_mov_b64 s[82:83], -1
	s_cbranch_scc0 .LBB0_896
	s_and_b64 vcc, exec, s[82:83]
	s_cbranch_vccz .LBB0_892

; __device__ __forceinline__ unsigned xb_ld(unsigned* p)              { return __hip_atomic_load(p, __ATOMIC_RELAXED, __HIP_MEMORY_SCOPE_AGENT); }
; __device__ __forceinline__ unsigned xb_add(unsigned* p, unsigned v) { return __hip_atomic_fetch_add(p, v, __ATOMIC_RELAXED, __HIP_MEMORY_SCOPE_AGENT); }
; #define XB_SPIN(cond, bar) do { unsigned _sp = 0; while (cond) { __builtin_amdgcn_s_sleep(1); \
;     if ((++_sp & 255u) == 0u) { if (xb_ld(&(bar)[XB_TMO])) break; if (_sp > XB_SPIN_CAP) { atomicAdd(&(bar)[XB_TMO], 1u); break; } } } } while (0)
; __device__ __forceinline__ void xcd_barrier(const XcdBarrier& b) {
;     ...
;             else XB_SPIN(xb_ld(&bar[XB_TOPGEN]) == tg, bar);
;             __builtin_amdgcn_fence(__ATOMIC_ACQUIRE, "agent");
;             xb_add(&bar[XB_XGEN(b.x)], 1u);
;             asm volatile("s_waitcnt vmcnt(0)" ::: "memory");
;         } else {
;             XB_SPIN(xb_ld(&bar[XB_XGEN(b.x)]) == gen, bar);
.LBB0_949:
	s_and_b32 s11, s10, 0xff
	s_mov_b64 s[68:69], -1
	s_cmp_lg_u32 s11, 0
	s_mov_b64 s[72:73], -1
	s_cbranch_scc0 .LBB0_952
	s_and_b64 vcc, exec, s[72:73]
	s_cbranch_vccz .LBB0_948
